# P0 gate/up and w_in transposes: all 32 row loads plus the gain vector in flight at once instead of one load at a time
# speedup vs baseline: 1.0190x; 1.0054x over previous
; #define LAS __attribute__((address_space(3)))
; __device__ __forceinline__ void transpose_item(const float* W, int K, int N, bf16* WT, int kb, int n0, int drow0, LAS float* scr, int lane, const float* gk = nullptr) {
;     const int k0 = 64 * kb;
; #pragma unroll 8
;     for (int i = 0; i < 32; ++i) { const int kk = 2 * i + (lane >> 5); scr[kk * 33 + (lane & 31)] = W[(size_t)(k0 + kk) * N + n0 + (lane & 31)] * (gk ? gk[k0 + kk] : 1.f); }
.LBB0_41:
	v_readfirstlane_b32 s98, v38
	s_nop 3
	s_add_u32 s98, s10, s98
	s_addc_u32 s99, s11, 0
	s_mov_b32 s100, 0
	s_mov_b32 s101, -1
	v_mov_b32_e32 v144, 0
	s_andn2_b64 vcc, exec, s[6:7]
	s_cbranch_vccnz .Lt2_nogk
	global_load_dwordx4 v[164:167], v144, s[98:99]
	global_load_dwordx4 v[168:171], v144, s[98:99] offset:16
	global_load_dwordx4 v[172:175], v144, s[98:99] offset:32
	global_load_dwordx4 v[176:179], v144, s[98:99] offset:48
	global_load_dwordx4 v[180:183], v144, s[98:99] offset:64
	global_load_dwordx4 v[184:187], v144, s[98:99] offset:80
	global_load_dwordx4 v[188:191], v144, s[98:99] offset:96
	global_load_dwordx4 v[192:195], v144, s[98:99] offset:112
	global_load_dwordx4 v[196:199], v144, s[98:99] offset:128
	global_load_dwordx4 v[200:203], v144, s[98:99] offset:144
	global_load_dwordx4 v[204:207], v144, s[98:99] offset:160
	global_load_dwordx4 v[208:211], v144, s[98:99] offset:176
	global_load_dwordx4 v[212:215], v144, s[98:99] offset:192
	global_load_dwordx4 v[216:219], v144, s[98:99] offset:208
	global_load_dwordx4 v[220:223], v144, s[98:99] offset:224
	global_load_dwordx4 v[224:227], v144, s[98:99] offset:240
	s_branch .Lt2_w
.Lt2_nogk:
	v_mov_b32_e32 v164, 1.0
	v_mov_b32_e32 v165, 1.0
	v_mov_b32_e32 v166, 1.0
	v_mov_b32_e32 v167, 1.0
	v_mov_b32_e32 v168, 1.0
	v_mov_b32_e32 v169, 1.0
	v_mov_b32_e32 v170, 1.0
	v_mov_b32_e32 v171, 1.0
	v_mov_b32_e32 v172, 1.0
	v_mov_b32_e32 v173, 1.0
	v_mov_b32_e32 v174, 1.0
	v_mov_b32_e32 v175, 1.0
	v_mov_b32_e32 v176, 1.0
	v_mov_b32_e32 v177, 1.0
	v_mov_b32_e32 v178, 1.0
	v_mov_b32_e32 v179, 1.0
	v_mov_b32_e32 v180, 1.0
	v_mov_b32_e32 v181, 1.0
	v_mov_b32_e32 v182, 1.0
	v_mov_b32_e32 v183, 1.0
	v_mov_b32_e32 v184, 1.0
	v_mov_b32_e32 v185, 1.0
	v_mov_b32_e32 v186, 1.0
	v_mov_b32_e32 v187, 1.0
	v_mov_b32_e32 v188, 1.0
	v_mov_b32_e32 v189, 1.0
	v_mov_b32_e32 v190, 1.0
	v_mov_b32_e32 v191, 1.0
	v_mov_b32_e32 v192, 1.0
	v_mov_b32_e32 v193, 1.0
	v_mov_b32_e32 v194, 1.0
	v_mov_b32_e32 v195, 1.0
	v_mov_b32_e32 v196, 1.0
	v_mov_b32_e32 v197, 1.0
	v_mov_b32_e32 v198, 1.0
	v_mov_b32_e32 v199, 1.0
	v_mov_b32_e32 v200, 1.0
	v_mov_b32_e32 v201, 1.0
	v_mov_b32_e32 v202, 1.0
	v_mov_b32_e32 v203, 1.0
	v_mov_b32_e32 v204, 1.0
	v_mov_b32_e32 v205, 1.0
	v_mov_b32_e32 v206, 1.0
	v_mov_b32_e32 v207, 1.0
	v_mov_b32_e32 v208, 1.0
	v_mov_b32_e32 v209, 1.0
	v_mov_b32_e32 v210, 1.0
	v_mov_b32_e32 v211, 1.0
	v_mov_b32_e32 v212, 1.0
	v_mov_b32_e32 v213, 1.0
	v_mov_b32_e32 v214, 1.0
	v_mov_b32_e32 v215, 1.0
	v_mov_b32_e32 v216, 1.0
	v_mov_b32_e32 v217, 1.0
	v_mov_b32_e32 v218, 1.0
	v_mov_b32_e32 v219, 1.0
	v_mov_b32_e32 v220, 1.0
	v_mov_b32_e32 v221, 1.0
	v_mov_b32_e32 v222, 1.0
	v_mov_b32_e32 v223, 1.0
	v_mov_b32_e32 v224, 1.0
	v_mov_b32_e32 v225, 1.0
	v_mov_b32_e32 v226, 1.0
	v_mov_b32_e32 v227, 1.0
.Lt2_w:
	v_lshl_add_u64 v[142:143], v[52:53], 0, s[8:9]
	global_load_dword v110, v[142:143], off
	v_lshl_add_u64 v[146:147], v[50:51], 0, s[8:9]
	global_load_dword v111, v[146:147], off
	v_lshl_add_u64 v[142:143], v[48:49], 0, s[8:9]
	global_load_dword v112, v[142:143], off
	v_lshl_add_u64 v[146:147], v[46:47], 0, s[8:9]
	global_load_dword v113, v[146:147], off
	v_lshl_add_u64 v[142:143], v[44:45], 0, s[8:9]
	global_load_dword v114, v[142:143], off
	v_lshl_add_u64 v[146:147], v[42:43], 0, s[8:9]
	global_load_dword v115, v[146:147], off
	v_lshl_add_u64 v[142:143], v[40:41], 0, s[8:9]
	global_load_dword v116, v[142:143], off
	v_lshl_add_u64 v[146:147], v[36:37], 0, s[8:9]
	global_load_dword v117, v[146:147], off
	s_add_u32 s8, s8, 0x34000
	s_addc_u32 s9, s9, 0
	v_lshl_add_u64 v[142:143], v[52:53], 0, s[8:9]
	global_load_dword v118, v[142:143], off
	v_lshl_add_u64 v[146:147], v[50:51], 0, s[8:9]
	global_load_dword v119, v[146:147], off
	v_lshl_add_u64 v[142:143], v[48:49], 0, s[8:9]
	global_load_dword v120, v[142:143], off
	v_lshl_add_u64 v[146:147], v[46:47], 0, s[8:9]
	global_load_dword v121, v[146:147], off
	v_lshl_add_u64 v[142:143], v[44:45], 0, s[8:9]
	global_load_dword v122, v[142:143], off
	v_lshl_add_u64 v[146:147], v[42:43], 0, s[8:9]
	global_load_dword v123, v[146:147], off
	v_lshl_add_u64 v[142:143], v[40:41], 0, s[8:9]
	global_load_dword v124, v[142:143], off
	v_lshl_add_u64 v[146:147], v[36:37], 0, s[8:9]
	global_load_dword v125, v[146:147], off
	s_add_u32 s8, s8, 0x34000
	s_addc_u32 s9, s9, 0
	v_lshl_add_u64 v[142:143], v[52:53], 0, s[8:9]
	global_load_dword v126, v[142:143], off
	v_lshl_add_u64 v[146:147], v[50:51], 0, s[8:9]
	global_load_dword v127, v[146:147], off
	v_lshl_add_u64 v[142:143], v[48:49], 0, s[8:9]
	global_load_dword v128, v[142:143], off
	v_lshl_add_u64 v[146:147], v[46:47], 0, s[8:9]
	global_load_dword v129, v[146:147], off
	v_lshl_add_u64 v[142:143], v[44:45], 0, s[8:9]
	global_load_dword v130, v[142:143], off
	v_lshl_add_u64 v[146:147], v[42:43], 0, s[8:9]
	global_load_dword v131, v[146:147], off
	v_lshl_add_u64 v[142:143], v[40:41], 0, s[8:9]
	global_load_dword v132, v[142:143], off
	v_lshl_add_u64 v[146:147], v[36:37], 0, s[8:9]
	global_load_dword v133, v[146:147], off
	s_add_u32 s8, s8, 0x34000
	s_addc_u32 s9, s9, 0
	v_lshl_add_u64 v[142:143], v[52:53], 0, s[8:9]
	global_load_dword v134, v[142:143], off
	v_lshl_add_u64 v[146:147], v[50:51], 0, s[8:9]
	global_load_dword v135, v[146:147], off
	v_lshl_add_u64 v[142:143], v[48:49], 0, s[8:9]
	global_load_dword v136, v[142:143], off
	v_lshl_add_u64 v[146:147], v[46:47], 0, s[8:9]
	global_load_dword v137, v[146:147], off
	v_lshl_add_u64 v[142:143], v[44:45], 0, s[8:9]
	global_load_dword v138, v[142:143], off
	v_lshl_add_u64 v[146:147], v[42:43], 0, s[8:9]
	global_load_dword v139, v[146:147], off
	v_lshl_add_u64 v[142:143], v[40:41], 0, s[8:9]
	global_load_dword v140, v[142:143], off
	v_lshl_add_u64 v[146:147], v[36:37], 0, s[8:9]
	global_load_dword v141, v[146:147], off
	s_add_u32 s8, s8, 0x34000
	s_addc_u32 s9, s9, 0
	s_waitcnt vmcnt(31)
; __device__ __forceinline__ void transpose_item(const float* W, int K, int N, bf16* WT, int kb, int n0, int drow0, LAS float* scr, int lane, const float* gk = nullptr) {
;     ...
;     for (int i = 0; i < 32; ++i) { const int kk = 2 * i + (lane >> 5); scr[kk * 33 + (lane & 31)] = W[(size_t)(k0 + kk) * N + n0 + (lane & 31)] * (gk ? gk[k0 + kk] : 1.f); }
	v_cndmask_b32_e64 v148, v164, v165, s[100:101]
	v_mul_f32_e32 v110, v110, v148
	ds_write_b32 v35, v110
	s_waitcnt vmcnt(30)
	v_cndmask_b32_e64 v148, v166, v167, s[100:101]
	v_mul_f32_e32 v111, v111, v148
	ds_write_b32 v35, v111 offset:264
	s_waitcnt vmcnt(29)
	v_cndmask_b32_e64 v148, v168, v169, s[100:101]
	v_mul_f32_e32 v112, v112, v148
	ds_write_b32 v35, v112 offset:528
	s_waitcnt vmcnt(28)
	v_cndmask_b32_e64 v148, v170, v171, s[100:101]
	v_mul_f32_e32 v113, v113, v148
	ds_write_b32 v35, v113 offset:792
	s_waitcnt vmcnt(27)
	v_cndmask_b32_e64 v148, v172, v173, s[100:101]
	v_mul_f32_e32 v114, v114, v148
	ds_write_b32 v35, v114 offset:1056
	s_waitcnt vmcnt(26)
	v_cndmask_b32_e64 v148, v174, v175, s[100:101]
	v_mul_f32_e32 v115, v115, v148
	ds_write_b32 v35, v115 offset:1320
	s_waitcnt vmcnt(25)
	v_cndmask_b32_e64 v148, v176, v177, s[100:101]
	v_mul_f32_e32 v116, v116, v148
	ds_write_b32 v35, v116 offset:1584
	s_waitcnt vmcnt(24)
	v_cndmask_b32_e64 v148, v178, v179, s[100:101]
	v_mul_f32_e32 v117, v117, v148
	ds_write_b32 v35, v117 offset:1848
	s_waitcnt vmcnt(23)
	v_cndmask_b32_e64 v148, v180, v181, s[100:101]
	v_mul_f32_e32 v118, v118, v148
	ds_write_b32 v35, v118 offset:2112
	s_waitcnt vmcnt(22)
	v_cndmask_b32_e64 v148, v182, v183, s[100:101]
	v_mul_f32_e32 v119, v119, v148
	ds_write_b32 v35, v119 offset:2376
	s_waitcnt vmcnt(21)
	v_cndmask_b32_e64 v148, v184, v185, s[100:101]
	v_mul_f32_e32 v120, v120, v148
	ds_write_b32 v35, v120 offset:2640
	s_waitcnt vmcnt(20)
	v_cndmask_b32_e64 v148, v186, v187, s[100:101]
	v_mul_f32_e32 v121, v121, v148
	ds_write_b32 v35, v121 offset:2904
	s_waitcnt vmcnt(19)
	v_cndmask_b32_e64 v148, v188, v189, s[100:101]
	v_mul_f32_e32 v122, v122, v148
	ds_write_b32 v35, v122 offset:3168
	s_waitcnt vmcnt(18)
	v_cndmask_b32_e64 v148, v190, v191, s[100:101]
	v_mul_f32_e32 v123, v123, v148
	ds_write_b32 v35, v123 offset:3432
	s_waitcnt vmcnt(17)
	v_cndmask_b32_e64 v148, v192, v193, s[100:101]
	v_mul_f32_e32 v124, v124, v148
	ds_write_b32 v35, v124 offset:3696
	s_waitcnt vmcnt(16)
	v_cndmask_b32_e64 v148, v194, v195, s[100:101]
	v_mul_f32_e32 v125, v125, v148
	ds_write_b32 v35, v125 offset:3960
	s_waitcnt vmcnt(15)
	v_cndmask_b32_e64 v148, v196, v197, s[100:101]
	v_mul_f32_e32 v126, v126, v148
	ds_write_b32 v35, v126 offset:4224
	s_waitcnt vmcnt(14)
	v_cndmask_b32_e64 v148, v198, v199, s[100:101]
	v_mul_f32_e32 v127, v127, v148
	ds_write_b32 v35, v127 offset:4488
	s_waitcnt vmcnt(13)
	v_cndmask_b32_e64 v148, v200, v201, s[100:101]
	v_mul_f32_e32 v128, v128, v148
	ds_write_b32 v35, v128 offset:4752
	s_waitcnt vmcnt(12)
	v_cndmask_b32_e64 v148, v202, v203, s[100:101]
	v_mul_f32_e32 v129, v129, v148
	ds_write_b32 v35, v129 offset:5016
	s_waitcnt vmcnt(11)
	v_cndmask_b32_e64 v148, v204, v205, s[100:101]
	v_mul_f32_e32 v130, v130, v148
	ds_write_b32 v35, v130 offset:5280
	s_waitcnt vmcnt(10)
	v_cndmask_b32_e64 v148, v206, v207, s[100:101]
	v_mul_f32_e32 v131, v131, v148
	ds_write_b32 v35, v131 offset:5544
	s_waitcnt vmcnt(9)
	v_cndmask_b32_e64 v148, v208, v209, s[100:101]
	v_mul_f32_e32 v132, v132, v148
	ds_write_b32 v35, v132 offset:5808
	s_waitcnt vmcnt(8)
	v_cndmask_b32_e64 v148, v210, v211, s[100:101]
	v_mul_f32_e32 v133, v133, v148
	ds_write_b32 v35, v133 offset:6072
	s_waitcnt vmcnt(7)
	v_cndmask_b32_e64 v148, v212, v213, s[100:101]
	v_mul_f32_e32 v134, v134, v148
	ds_write_b32 v35, v134 offset:6336
	s_waitcnt vmcnt(6)
	v_cndmask_b32_e64 v148, v214, v215, s[100:101]
	v_mul_f32_e32 v135, v135, v148
	ds_write_b32 v35, v135 offset:6600
	s_waitcnt vmcnt(5)
	v_cndmask_b32_e64 v148, v216, v217, s[100:101]
	v_mul_f32_e32 v136, v136, v148
	ds_write_b32 v35, v136 offset:6864
	s_waitcnt vmcnt(4)
	v_cndmask_b32_e64 v148, v218, v219, s[100:101]
	v_mul_f32_e32 v137, v137, v148
	ds_write_b32 v35, v137 offset:7128
	s_waitcnt vmcnt(3)
	v_cndmask_b32_e64 v148, v220, v221, s[100:101]
	v_mul_f32_e32 v138, v138, v148
	ds_write_b32 v35, v138 offset:7392
	s_waitcnt vmcnt(2)
	v_cndmask_b32_e64 v148, v222, v223, s[100:101]
	v_mul_f32_e32 v139, v139, v148
	ds_write_b32 v35, v139 offset:7656
	s_waitcnt vmcnt(1)
	v_cndmask_b32_e64 v148, v224, v225, s[100:101]
	v_mul_f32_e32 v140, v140, v148
	ds_write_b32 v35, v140 offset:7920
	s_waitcnt vmcnt(0)
	v_cndmask_b32_e64 v148, v226, v227, s[100:101]
	v_mul_f32_e32 v141, v141, v148
	ds_write_b32 v35, v141 offset:8184
	v_add_u32_e32 v35, 0x2100, v35
	s_add_u32 s10, s10, 0x100
	s_addc_u32 s11, s11, 0
	s_branch .LBB0_57

; #define LAS __attribute__((address_space(3)))
; __device__ __forceinline__ void transpose_item(const float* W, int K, int N, bf16* WT, int kb, int n0, int drow0, LAS float* scr, int lane, const float* gk = nullptr) {
;     const int k0 = 64 * kb;
; #pragma unroll 8
;     for (int i = 0; i < 32; ++i) { const int kk = 2 * i + (lane >> 5); scr[kk * 33 + (lane & 31)] = W[(size_t)(k0 + kk) * N + n0 + (lane & 31)] * (gk ? gk[k0 + kk] : 1.f); }
.LBB0_67:
	s_lshl_b64 s[98:99], s[10:11], 2
	s_add_u32 s98, s24, s98
	s_addc_u32 s99, s25, s99
	s_mov_b32 s100, 0
	s_mov_b32 s101, -1
	v_mov_b32_e32 v144, 0
	s_andn2_b64 vcc, exec, s[16:17]
	s_cbranch_vccnz .Lt1_nogk
	global_load_dwordx4 v[164:167], v144, s[98:99]
	global_load_dwordx4 v[168:171], v144, s[98:99] offset:16
	global_load_dwordx4 v[172:175], v144, s[98:99] offset:32
	global_load_dwordx4 v[176:179], v144, s[98:99] offset:48
	global_load_dwordx4 v[180:183], v144, s[98:99] offset:64
	global_load_dwordx4 v[184:187], v144, s[98:99] offset:80
	global_load_dwordx4 v[188:191], v144, s[98:99] offset:96
	global_load_dwordx4 v[192:195], v144, s[98:99] offset:112
	global_load_dwordx4 v[196:199], v144, s[98:99] offset:128
	global_load_dwordx4 v[200:203], v144, s[98:99] offset:144
	global_load_dwordx4 v[204:207], v144, s[98:99] offset:160
	global_load_dwordx4 v[208:211], v144, s[98:99] offset:176
	global_load_dwordx4 v[212:215], v144, s[98:99] offset:192
	global_load_dwordx4 v[216:219], v144, s[98:99] offset:208
	global_load_dwordx4 v[220:223], v144, s[98:99] offset:224
	global_load_dwordx4 v[224:227], v144, s[98:99] offset:240
	s_branch .Lt1_w

; __device__ __forceinline__ void transpose_item(const float* W, int K, int N, bf16* WT, int kb, int n0, int drow0, LAS float* scr, int lane, const float* gk = nullptr) {
;     ...
;     for (int i = 0; i < 32; ++i) { const int kk = 2 * i + (lane >> 5); scr[kk * 33 + (lane & 31)] = W[(size_t)(k0 + kk) * N + n0 + (lane & 31)] * (gk ? gk[k0 + kk] : 1.f); }
.Lt1_w:
	v_lshl_add_u64 v[142:143], v[38:39], 0, s[14:15]
	global_load_dword v110, v[142:143], off
	v_lshl_add_u64 v[146:147], v[52:53], 0, s[14:15]
	global_load_dword v111, v[146:147], off
	v_lshl_add_u64 v[142:143], v[50:51], 0, s[14:15]
	global_load_dword v112, v[142:143], off
	v_lshl_add_u64 v[146:147], v[48:49], 0, s[14:15]
	global_load_dword v113, v[146:147], off
	v_lshl_add_u64 v[142:143], v[46:47], 0, s[14:15]
	global_load_dword v114, v[142:143], off
	v_lshl_add_u64 v[146:147], v[44:45], 0, s[14:15]
	global_load_dword v115, v[146:147], off
	v_lshl_add_u64 v[142:143], v[40:41], 0, s[14:15]
	global_load_dword v116, v[142:143], off
	v_lshl_add_u64 v[146:147], v[36:37], 0, s[14:15]
	global_load_dword v117, v[146:147], off
	s_add_u32 s14, s14, 0x2c000
	s_addc_u32 s15, s15, 0
	v_lshl_add_u64 v[142:143], v[38:39], 0, s[14:15]
	global_load_dword v118, v[142:143], off
	v_lshl_add_u64 v[146:147], v[52:53], 0, s[14:15]
	global_load_dword v119, v[146:147], off
	v_lshl_add_u64 v[142:143], v[50:51], 0, s[14:15]
	global_load_dword v120, v[142:143], off
	v_lshl_add_u64 v[146:147], v[48:49], 0, s[14:15]
	global_load_dword v121, v[146:147], off
	v_lshl_add_u64 v[142:143], v[46:47], 0, s[14:15]
	global_load_dword v122, v[142:143], off
	v_lshl_add_u64 v[146:147], v[44:45], 0, s[14:15]
	global_load_dword v123, v[146:147], off
	v_lshl_add_u64 v[142:143], v[40:41], 0, s[14:15]
	global_load_dword v124, v[142:143], off
	v_lshl_add_u64 v[146:147], v[36:37], 0, s[14:15]
	global_load_dword v125, v[146:147], off
	s_add_u32 s14, s14, 0x2c000
	s_addc_u32 s15, s15, 0
	v_lshl_add_u64 v[142:143], v[38:39], 0, s[14:15]
	global_load_dword v126, v[142:143], off
	v_lshl_add_u64 v[146:147], v[52:53], 0, s[14:15]
	global_load_dword v127, v[146:147], off
	v_lshl_add_u64 v[142:143], v[50:51], 0, s[14:15]
	global_load_dword v128, v[142:143], off
	v_lshl_add_u64 v[146:147], v[48:49], 0, s[14:15]
	global_load_dword v129, v[146:147], off
	v_lshl_add_u64 v[142:143], v[46:47], 0, s[14:15]
	global_load_dword v130, v[142:143], off
	v_lshl_add_u64 v[146:147], v[44:45], 0, s[14:15]
	global_load_dword v131, v[146:147], off
	v_lshl_add_u64 v[142:143], v[40:41], 0, s[14:15]
	global_load_dword v132, v[142:143], off
	v_lshl_add_u64 v[146:147], v[36:37], 0, s[14:15]
	global_load_dword v133, v[146:147], off
	s_add_u32 s14, s14, 0x2c000
	s_addc_u32 s15, s15, 0
	v_lshl_add_u64 v[142:143], v[38:39], 0, s[14:15]
	global_load_dword v134, v[142:143], off
	v_lshl_add_u64 v[146:147], v[52:53], 0, s[14:15]
	global_load_dword v135, v[146:147], off
	v_lshl_add_u64 v[142:143], v[50:51], 0, s[14:15]
	global_load_dword v136, v[142:143], off
	v_lshl_add_u64 v[146:147], v[48:49], 0, s[14:15]
	global_load_dword v137, v[146:147], off
	v_lshl_add_u64 v[142:143], v[46:47], 0, s[14:15]
	global_load_dword v138, v[142:143], off
	v_lshl_add_u64 v[146:147], v[44:45], 0, s[14:15]
	global_load_dword v139, v[146:147], off
	v_lshl_add_u64 v[142:143], v[40:41], 0, s[14:15]
	global_load_dword v140, v[142:143], off
	v_lshl_add_u64 v[146:147], v[36:37], 0, s[14:15]
	global_load_dword v141, v[146:147], off
	s_add_u32 s14, s14, 0x2c000
	s_addc_u32 s15, s15, 0
	s_waitcnt vmcnt(31)
	v_cndmask_b32_e64 v148, v164, v165, s[100:101]
	v_mul_f32_e32 v110, v110, v148
	ds_write_b32 v4, v110
	s_waitcnt vmcnt(30)
	v_cndmask_b32_e64 v148, v166, v167, s[100:101]
	v_mul_f32_e32 v111, v111, v148
	ds_write_b32 v4, v111 offset:264
	s_waitcnt vmcnt(29)
	v_cndmask_b32_e64 v148, v168, v169, s[100:101]
	v_mul_f32_e32 v112, v112, v148
	ds_write_b32 v4, v112 offset:528
	s_waitcnt vmcnt(28)
	v_cndmask_b32_e64 v148, v170, v171, s[100:101]
	v_mul_f32_e32 v113, v113, v148
	ds_write_b32 v4, v113 offset:792
	s_waitcnt vmcnt(27)
	v_cndmask_b32_e64 v148, v172, v173, s[100:101]
	v_mul_f32_e32 v114, v114, v148
	ds_write_b32 v4, v114 offset:1056
	s_waitcnt vmcnt(26)
; __device__ __forceinline__ void transpose_item(const float* W, int K, int N, bf16* WT, int kb, int n0, int drow0, LAS float* scr, int lane, const float* gk = nullptr) {
;     ...
;     for (int i = 0; i < 32; ++i) { const int kk = 2 * i + (lane >> 5); scr[kk * 33 + (lane & 31)] = W[(size_t)(k0 + kk) * N + n0 + (lane & 31)] * (gk ? gk[k0 + kk] : 1.f); }
	v_cndmask_b32_e64 v148, v174, v175, s[100:101]
	v_mul_f32_e32 v115, v115, v148
	ds_write_b32 v4, v115 offset:1320
	s_waitcnt vmcnt(25)
	v_cndmask_b32_e64 v148, v176, v177, s[100:101]
	v_mul_f32_e32 v116, v116, v148
	ds_write_b32 v4, v116 offset:1584
	s_waitcnt vmcnt(24)
	v_cndmask_b32_e64 v148, v178, v179, s[100:101]
	v_mul_f32_e32 v117, v117, v148
	ds_write_b32 v4, v117 offset:1848
	s_waitcnt vmcnt(23)
	v_cndmask_b32_e64 v148, v180, v181, s[100:101]
	v_mul_f32_e32 v118, v118, v148
	ds_write_b32 v4, v118 offset:2112
	s_waitcnt vmcnt(22)
	v_cndmask_b32_e64 v148, v182, v183, s[100:101]
	v_mul_f32_e32 v119, v119, v148
	ds_write_b32 v4, v119 offset:2376
	s_waitcnt vmcnt(21)
	v_cndmask_b32_e64 v148, v184, v185, s[100:101]
	v_mul_f32_e32 v120, v120, v148
	ds_write_b32 v4, v120 offset:2640
	s_waitcnt vmcnt(20)
	v_cndmask_b32_e64 v148, v186, v187, s[100:101]
	v_mul_f32_e32 v121, v121, v148
	ds_write_b32 v4, v121 offset:2904
	s_waitcnt vmcnt(19)
	v_cndmask_b32_e64 v148, v188, v189, s[100:101]
	v_mul_f32_e32 v122, v122, v148
	ds_write_b32 v4, v122 offset:3168
	s_waitcnt vmcnt(18)
	v_cndmask_b32_e64 v148, v190, v191, s[100:101]
	v_mul_f32_e32 v123, v123, v148
	ds_write_b32 v4, v123 offset:3432
	s_waitcnt vmcnt(17)
	v_cndmask_b32_e64 v148, v192, v193, s[100:101]
	v_mul_f32_e32 v124, v124, v148
	ds_write_b32 v4, v124 offset:3696
	s_waitcnt vmcnt(16)
	v_cndmask_b32_e64 v148, v194, v195, s[100:101]
	v_mul_f32_e32 v125, v125, v148
	ds_write_b32 v4, v125 offset:3960
	s_waitcnt vmcnt(15)
	v_cndmask_b32_e64 v148, v196, v197, s[100:101]
	v_mul_f32_e32 v126, v126, v148
	ds_write_b32 v4, v126 offset:4224
	s_waitcnt vmcnt(14)
	v_cndmask_b32_e64 v148, v198, v199, s[100:101]
	v_mul_f32_e32 v127, v127, v148
	ds_write_b32 v4, v127 offset:4488
	s_waitcnt vmcnt(13)
	v_cndmask_b32_e64 v148, v200, v201, s[100:101]
	v_mul_f32_e32 v128, v128, v148
	ds_write_b32 v4, v128 offset:4752
	s_waitcnt vmcnt(12)
	v_cndmask_b32_e64 v148, v202, v203, s[100:101]
	v_mul_f32_e32 v129, v129, v148
	ds_write_b32 v4, v129 offset:5016
	s_waitcnt vmcnt(11)
	v_cndmask_b32_e64 v148, v204, v205, s[100:101]
	v_mul_f32_e32 v130, v130, v148
	ds_write_b32 v4, v130 offset:5280
	s_waitcnt vmcnt(10)
	v_cndmask_b32_e64 v148, v206, v207, s[100:101]
	v_mul_f32_e32 v131, v131, v148
	ds_write_b32 v4, v131 offset:5544
	s_waitcnt vmcnt(9)
	v_cndmask_b32_e64 v148, v208, v209, s[100:101]
	v_mul_f32_e32 v132, v132, v148
	ds_write_b32 v4, v132 offset:5808
	s_waitcnt vmcnt(8)
	v_cndmask_b32_e64 v148, v210, v211, s[100:101]
	v_mul_f32_e32 v133, v133, v148
	ds_write_b32 v4, v133 offset:6072
	s_waitcnt vmcnt(7)
	v_cndmask_b32_e64 v148, v212, v213, s[100:101]
	v_mul_f32_e32 v134, v134, v148
	ds_write_b32 v4, v134 offset:6336
	s_waitcnt vmcnt(6)
	v_cndmask_b32_e64 v148, v214, v215, s[100:101]
	v_mul_f32_e32 v135, v135, v148
	ds_write_b32 v4, v135 offset:6600
	s_waitcnt vmcnt(5)
	v_cndmask_b32_e64 v148, v216, v217, s[100:101]
	v_mul_f32_e32 v136, v136, v148
	ds_write_b32 v4, v136 offset:6864
	s_waitcnt vmcnt(4)
	v_cndmask_b32_e64 v148, v218, v219, s[100:101]
	v_mul_f32_e32 v137, v137, v148
	ds_write_b32 v4, v137 offset:7128
	s_waitcnt vmcnt(3)
	v_cndmask_b32_e64 v148, v220, v221, s[100:101]
	v_mul_f32_e32 v138, v138, v148
	ds_write_b32 v4, v138 offset:7392
	s_waitcnt vmcnt(2)
	v_cndmask_b32_e64 v148, v222, v223, s[100:101]
	v_mul_f32_e32 v139, v139, v148
	ds_write_b32 v4, v139 offset:7656
	s_waitcnt vmcnt(1)
	v_cndmask_b32_e64 v148, v224, v225, s[100:101]
	v_mul_f32_e32 v140, v140, v148
	ds_write_b32 v4, v140 offset:7920
	s_waitcnt vmcnt(0)
	v_cndmask_b32_e64 v148, v226, v227, s[100:101]
	v_mul_f32_e32 v141, v141, v148
	ds_write_b32 v4, v141 offset:8184
	v_add_u32_e32 v4, 0x2100, v4
	v_lshl_add_u64 v[42:43], v[42:43], 0, 64
	v_lshl_add_u64 v[42:43], v[42:43], 0, 64
	v_lshl_add_u64 v[42:43], v[42:43], 0, 64
	v_lshl_add_u64 v[42:43], v[42:43], 0, 64
	s_branch .LBB0_8

; __global__ void __launch_bounds__(512, 2) fwd_kernel(Args args) {
;     extern __shared__ __attribute__((aligned(16))) unsigned char lds_raw[];
	.amdhsa_kernel _Z10fwd_kernel4Args
		.amdhsa_group_segment_fixed_size 0
		.amdhsa_private_segment_fixed_size 0
		.amdhsa_kernarg_size 496
		.amdhsa_user_sgpr_count 2
		.amdhsa_user_sgpr_dispatch_ptr 0
		.amdhsa_user_sgpr_queue_ptr 0
		.amdhsa_user_sgpr_kernarg_segment_ptr 1
		.amdhsa_user_sgpr_dispatch_id 0
		.amdhsa_user_sgpr_kernarg_preload_length 0
		.amdhsa_user_sgpr_kernarg_preload_offset 0
		.amdhsa_user_sgpr_private_segment_size 0
		.amdhsa_uses_dynamic_stack 0
		.amdhsa_enable_private_segment 0
		.amdhsa_system_sgpr_workgroup_id_x 1
		.amdhsa_system_sgpr_workgroup_id_y 0
		.amdhsa_system_sgpr_workgroup_id_z 0
		.amdhsa_system_sgpr_workgroup_info 0
		.amdhsa_system_vgpr_workitem_id 2
		.amdhsa_next_free_vgpr 254
		.amdhsa_next_free_sgpr 102
		.amdhsa_accum_offset 256
		.amdhsa_reserve_vcc 1
		.amdhsa_float_round_mode_32 0
		.amdhsa_float_round_mode_16_64 0
		.amdhsa_float_denorm_mode_32 3
		.amdhsa_float_denorm_mode_16_64 3
		.amdhsa_dx10_clamp 1
		.amdhsa_ieee_mode 1
		.amdhsa_fp16_overflow 0
		.amdhsa_tg_split 0
		.amdhsa_exception_fp_ieee_invalid_op 0
		.amdhsa_exception_fp_denorm_src 0
		.amdhsa_exception_fp_ieee_div_zero 0
		.amdhsa_exception_fp_ieee_overflow 0
		.amdhsa_exception_fp_ieee_underflow 0
		.amdhsa_exception_fp_ieee_inexact 0
		.amdhsa_exception_int_div_zero 0
	.end_amdhsa_kernel

; __global__ void __launch_bounds__(512, 2) fwd_kernel(Args args) {
;     extern __shared__ __attribute__((aligned(16))) unsigned char lds_raw[];
amdhsa.kernels:
  - .agpr_count:     0
    .args:
      - .offset:         0
        .size:           240
        .value_kind:     by_value
      - .offset:         240
        .size:           4
        .value_kind:     hidden_block_count_x
      - .offset:         244
        .size:           4
        .value_kind:     hidden_block_count_y
      - .offset:         248
        .size:           4
        .value_kind:     hidden_block_count_z
      - .offset:         252
        .size:           2
        .value_kind:     hidden_group_size_x
      - .offset:         254
        .size:           2
        .value_kind:     hidden_group_size_y
      - .offset:         256
        .size:           2
        .value_kind:     hidden_group_size_z
      - .offset:         258
        .size:           2
        .value_kind:     hidden_remainder_x
      - .offset:         260
        .size:           2
        .value_kind:     hidden_remainder_y
      - .offset:         262
        .size:           2
        .value_kind:     hidden_remainder_z
      - .offset:         280
        .size:           8
        .value_kind:     hidden_global_offset_x
      - .offset:         288
        .size:           8
        .value_kind:     hidden_global_offset_y
      - .offset:         296
        .size:           8
        .value_kind:     hidden_global_offset_z
      - .offset:         304
        .size:           2
        .value_kind:     hidden_grid_dims
      - .offset:         328
        .size:           8
        .value_kind:     hidden_multigrid_sync_arg
      - .offset:         360
        .size:           4
        .value_kind:     hidden_dynamic_lds_size
    .group_segment_fixed_size: 0
    .kernarg_segment_align: 8
    .kernarg_segment_size: 496
    .language:       OpenCL C
    .language_version:
      - 2
      - 0
    .max_flat_workgroup_size: 512
    .name:           _Z10fwd_kernel4Args
    .private_segment_fixed_size: 0
    .sgpr_count:     108
    .sgpr_spill_count: 58
    .symbol:         _Z10fwd_kernel4Args.kd
    .uniform_work_group_size: 1
    .uses_dynamic_stack: false
    .vgpr_count:     254
    .vgpr_spill_count: 0
    .wavefront_size: 64
